# stack28: SSD carried-state product double-buffers its LDS fragment reads (on top of stack27)
# baseline (speedup 1.0000x reference)
; DI float bf2f(unsigned h) { return __uint_as_float(h << 16); }
; DI unsigned pk2(float lo, float hi) { return pg8::cvt_pk_bf16(lo, hi); }
; DI unsigned short f2bf(float f) { return (unsigned short)(pg8::cvt_pk_bf16(f, 0.f) & 0xffffu); }
; DI void ssd_out_unit(const Params& P, int layer, int b, int c, char* lds, int tid) {
;     ...
;     for (int g = 0; g < 2; ++g) {
;         __syncthreads();
; #pragma unroll
;         for (int i = 0; i < 4; ++i) { const int q = tid + 512 * i, l = q >> 4, n0 = (q & 15) * 8;
;             *(u32x4*)(BM + l * SP + n0) = *(const u32x4*)(SSDB + (size_t)(R0 + l) * 768 + 256 + 128 * g + n0);
;             *(u32x4*)(CM + l * SP + n0) = *(const u32x4*)(SSDB + (size_t)(R0 + l) * 768 + 512 + 128 * g + n0); }
; #pragma unroll
;         for (int hs = 0; hs < 2; ++hs) { const int h = 2 * g + hs;
; #pragma unroll
;             for (int i = 0; i < 2; ++i) { const int q = tid + 512 * i, l = q & 127, p0 = (q >> 7) * 8;
;                 const u32x4 v = *(const u32x4*)(SSDB + (size_t)(R0 + l) * 768 + 64 * h + p0); const float f = dtl[h * CH + l];
;                 bf16_t* d = XT[hs] + p0 * SP + l;
;                 d[0] = f2bf(bf2f(v.x & 0xffffu) * f); d[SP] = f2bf(bf2f(v.x >> 16) * f); d[2 * SP] = f2bf(bf2f(v.y & 0xffffu) * f); d[3 * SP] = f2bf(bf2f(v.y >> 16) * f);
;                 d[4 * SP] = f2bf(bf2f(v.z & 0xffffu) * f); d[5 * SP] = f2bf(bf2f(v.z >> 16) * f); d[6 * SP] = f2bf(bf2f(v.w & 0xffffu) * f); d[7 * SP] = f2bf(bf2f(v.w >> 16) * f); }
;             const float* sp = ST + ((size_t)((b * NCHUNK + c) * 4 + h)) * 8192;
; #pragma unroll
;             for (int i = 0; i < 4; ++i) { const int q = tid + 512 * i, p = q >> 5, n0 = (q & 31) * 4; const f32x4 v = *(const f32x4*)(sp + p * 128 + n0);
;                 u32x2 w; w.x = pk2(v.x, v.y); w.y = pk2(v.z, v.w); *(u32x2*)(PV[hs] + p * SP + n0) = w; } }
.LBB0_369:
	s_lshl_b32 s62, s5, 8
	s_lshl_b32 s13, s5, 10
	s_lshl_b32 s16, s5, 1
	s_or_b32 s22, s16, s4
	s_ashr_i32 s23, s22, 31
	s_lshl_b64 s[22:23], s[22:23], 15
	s_or_b32 s16, s16, 1
	s_waitcnt lgkmcnt(0)
	s_barrier
	v_add_u32_e32 v191, s13, v148
	ds_read_b32 v236, v191
	v_lshl_add_u32 v191, s16, 9, v148
	ds_read_b32 v237, v191
	v_lshl_add_u64 v[2:3], v[96:97], 0, s[62:63]
	global_load_dwordx4 v[6:9], v[2:3], off offset:1024
	global_load_dwordx4 v[2:5], v[2:3], off offset:512
	v_lshl_add_u64 v[10:11], v[98:99], 0, s[62:63]
	global_load_dwordx4 v[14:17], v[10:11], off offset:1024
	global_load_dwordx4 v[10:13], v[10:11], off offset:512
	v_lshl_add_u64 v[18:19], v[100:101], 0, s[62:63]
	global_load_dwordx4 v[22:25], v[18:19], off offset:1024
	global_load_dwordx4 v[18:21], v[18:19], off offset:512
	v_lshl_add_u64 v[26:27], v[102:103], 0, s[62:63]
	global_load_dwordx4 v[30:33], v[26:27], off offset:1024
	global_load_dwordx4 v[26:29], v[26:27], off offset:512
	v_lshl_add_u64 v[216:217], v[92:93], 0, s[62:63]
	v_lshl_add_u64 v[34:35], v[216:217], 0, v[80:81]
	global_load_dwordx4 v[34:37], v[34:35], off
	v_lshl_add_u64 v[38:39], v[216:217], 0, v[82:83]
	global_load_dwordx4 v[38:41], v[38:39], off
	v_lshl_add_u64 v[216:217], v[54:55], 0, s[22:23]
	v_lshl_add_u64 v[42:43], v[216:217], 0, v[84:85]
	global_load_dwordx4 v[42:45], v[42:43], off
	v_lshl_add_u64 v[46:47], v[216:217], 0, v[86:87]
	global_load_dwordx4 v[46:49], v[46:47], off
	v_lshl_add_u64 v[220:221], v[216:217], 0, v[88:89]
	global_load_dwordx4 v[220:223], v[220:221], off
	v_lshl_add_u64 v[224:225], v[216:217], 0, v[90:91]
	global_load_dwordx4 v[224:227], v[224:225], off
	s_lshl_b32 s62, s16, 7
	v_lshl_add_u64 v[216:217], v[92:93], 0, s[62:63]
	v_lshl_add_u64 v[228:229], v[216:217], 0, v[80:81]
	global_load_dwordx4 v[228:231], v[228:229], off
	v_lshl_add_u64 v[232:233], v[216:217], 0, v[82:83]
	global_load_dwordx4 v[232:235], v[232:233], off
	s_or_b32 s22, s16, s4
	s_ashr_i32 s23, s22, 31
	s_lshl_b64 s[22:23], s[22:23], 15
	v_lshl_add_u64 v[216:217], v[54:55], 0, s[22:23]
	v_lshl_add_u64 v[244:245], v[216:217], 0, v[84:85]
	global_load_dwordx4 v[244:247], v[244:245], off
	v_lshl_add_u64 v[248:249], v[216:217], 0, v[86:87]
	global_load_dwordx4 v[248:251], v[248:249], off
	v_lshl_add_u64 v[252:253], v[216:217], 0, v[88:89]
	global_load_dwordx4 v[252:255], v[252:253], off
	v_lshl_add_u64 v[216:217], v[216:217], 0, v[90:91]
	global_load_dwordx4 v[216:219], v[216:217], off
	s_add_i32 s16, s13, 0
	s_add_i32 s16, s16, 0x22020
	v_lshl_add_u32 v174, v154, 2, s16
	s_waitcnt vmcnt(19)
	ds_write_b128 v58, v[6:9]
	s_waitcnt vmcnt(18)
	ds_write_b128 v58, v[2:5] offset:34816
	s_waitcnt vmcnt(17)
	ds_write_b128 v60, v[14:17]
	s_waitcnt vmcnt(16)
	ds_write_b128 v60, v[10:13] offset:34816
	s_waitcnt vmcnt(15)
	ds_write_b128 v62, v[22:25]
	s_waitcnt vmcnt(14)
	ds_write_b128 v62, v[18:21] offset:34816
	s_waitcnt vmcnt(13)
	ds_write_b128 v64, v[30:33]
	s_waitcnt vmcnt(12)
	ds_write_b128 v64, v[26:29] offset:34816
	s_waitcnt vmcnt(11)
	s_waitcnt lgkmcnt(0)
	v_lshlrev_b32_e32 v190, 16, v34
	v_mul_f32_e32 v190, v236, v190
	v_cvt_pk_bf16_f32 v190, v190, v1
	ds_write_b16 v65, v190
	v_and_b32_e32 v190, 0xffff0000, v34
	v_mul_f32_e32 v190, v236, v190
	v_cvt_pk_bf16_f32 v190, v190, v1
	ds_write_b16 v65, v190 offset:272
	v_lshlrev_b32_e32 v190, 16, v35
	v_mul_f32_e32 v190, v236, v190
	v_cvt_pk_bf16_f32 v190, v190, v1
	ds_write_b16 v65, v190 offset:544
	v_and_b32_e32 v190, 0xffff0000, v35
	v_mul_f32_e32 v190, v236, v190
	v_cvt_pk_bf16_f32 v190, v190, v1
	ds_write_b16 v65, v190 offset:816
	v_lshlrev_b32_e32 v190, 16, v36
	v_mul_f32_e32 v190, v236, v190
	v_cvt_pk_bf16_f32 v190, v190, v1
	ds_write_b16 v65, v190 offset:1088
	v_and_b32_e32 v190, 0xffff0000, v36
	v_mul_f32_e32 v190, v236, v190
	v_cvt_pk_bf16_f32 v190, v190, v1
	ds_write_b16 v65, v190 offset:1360
	v_lshlrev_b32_e32 v190, 16, v37
	v_mul_f32_e32 v190, v236, v190
	v_cvt_pk_bf16_f32 v190, v190, v1
	ds_write_b16 v65, v190 offset:1632
	v_and_b32_e32 v190, 0xffff0000, v37
	v_mul_f32_e32 v190, v236, v190
	v_cvt_pk_bf16_f32 v190, v190, v1
	ds_write_b16 v65, v190 offset:1904
	s_waitcnt vmcnt(10)
	v_lshlrev_b32_e32 v190, 16, v38
	v_mul_f32_e32 v190, v236, v190
	v_cvt_pk_bf16_f32 v190, v190, v1
	ds_write_b16 v156, v190
	v_and_b32_e32 v190, 0xffff0000, v38
	v_mul_f32_e32 v190, v236, v190
	v_cvt_pk_bf16_f32 v190, v190, v1
	ds_write_b16 v156, v190 offset:272
	v_lshlrev_b32_e32 v190, 16, v39
	v_mul_f32_e32 v190, v236, v190
	v_cvt_pk_bf16_f32 v190, v190, v1
	ds_write_b16 v156, v190 offset:544
	v_and_b32_e32 v190, 0xffff0000, v39
	v_mul_f32_e32 v190, v236, v190
	v_cvt_pk_bf16_f32 v190, v190, v1
	ds_write_b16 v156, v190 offset:816
	v_lshlrev_b32_e32 v190, 16, v40
	v_mul_f32_e32 v190, v236, v190
	v_cvt_pk_bf16_f32 v190, v190, v1
	ds_write_b16 v156, v190 offset:1088
	v_and_b32_e32 v190, 0xffff0000, v40
	v_mul_f32_e32 v190, v236, v190
	v_cvt_pk_bf16_f32 v190, v190, v1
	ds_write_b16 v156, v190 offset:1360
	v_lshlrev_b32_e32 v190, 16, v41
	v_mul_f32_e32 v190, v236, v190
	v_cvt_pk_bf16_f32 v190, v190, v1
	ds_write_b16 v156, v190 offset:1632
	v_and_b32_e32 v190, 0xffff0000, v41
	v_mul_f32_e32 v190, v236, v190
	v_cvt_pk_bf16_f32 v190, v190, v1
	ds_write_b16 v156, v190 offset:1904
	s_waitcnt vmcnt(9)
	v_cvt_pk_bf16_f32 v42, v42, v43
	v_cvt_pk_bf16_f32 v43, v44, v45
	ds_write_b64 v157, v[42:43]
	s_waitcnt vmcnt(8)
	v_cvt_pk_bf16_f32 v46, v46, v47
	v_cvt_pk_bf16_f32 v47, v48, v49
	ds_write_b64 v158, v[46:47]
	s_waitcnt vmcnt(7)
	v_cvt_pk_bf16_f32 v220, v220, v221
	v_cvt_pk_bf16_f32 v221, v222, v223
	ds_write_b64 v159, v[220:221]
	s_waitcnt vmcnt(6)
; DI float bf2f(unsigned h) { return __uint_as_float(h << 16); }
; DI unsigned pk2(float lo, float hi) { return pg8::cvt_pk_bf16(lo, hi); }
; DI unsigned short f2bf(float f) { return (unsigned short)(pg8::cvt_pk_bf16(f, 0.f) & 0xffffu); }
; DI void ssd_out_unit(const Params& P, int layer, int b, int c, char* lds, int tid) {
;     ...
;         for (int hs = 0; hs < 2; ++hs) { const int h = 2 * g + hs;
; #pragma unroll
;             for (int i = 0; i < 2; ++i) { const int q = tid + 512 * i, l = q & 127, p0 = (q >> 7) * 8;
;                 const u32x4 v = *(const u32x4*)(SSDB + (size_t)(R0 + l) * 768 + 64 * h + p0); const float f = dtl[h * CH + l];
;                 bf16_t* d = XT[hs] + p0 * SP + l;
;                 d[0] = f2bf(bf2f(v.x & 0xffffu) * f); d[SP] = f2bf(bf2f(v.x >> 16) * f); d[2 * SP] = f2bf(bf2f(v.y & 0xffffu) * f); d[3 * SP] = f2bf(bf2f(v.y >> 16) * f);
;                 d[4 * SP] = f2bf(bf2f(v.z & 0xffffu) * f); d[5 * SP] = f2bf(bf2f(v.z >> 16) * f); d[6 * SP] = f2bf(bf2f(v.w & 0xffffu) * f); d[7 * SP] = f2bf(bf2f(v.w >> 16) * f); }
;             const float* sp = ST + ((size_t)((b * NCHUNK + c) * 4 + h)) * 8192;
; #pragma unroll
;             for (int i = 0; i < 4; ++i) { const int q = tid + 512 * i, p = q >> 5, n0 = (q & 31) * 4; const f32x4 v = *(const f32x4*)(sp + p * 128 + n0);
;                 u32x2 w; w.x = pk2(v.x, v.y); w.y = pk2(v.z, v.w); *(u32x2*)(PV[hs] + p * SP + n0) = w; } }
;         __syncthreads();
	v_cvt_pk_bf16_f32 v224, v224, v225
	v_cvt_pk_bf16_f32 v225, v226, v227
	ds_write_b64 v160, v[224:225]
	s_waitcnt vmcnt(5)
	v_lshlrev_b32_e32 v190, 16, v228
	v_mul_f32_e32 v190, v237, v190
	v_cvt_pk_bf16_f32 v190, v190, v1
	ds_write_b16 v161, v190
	v_and_b32_e32 v190, 0xffff0000, v228
	v_mul_f32_e32 v190, v237, v190
	v_cvt_pk_bf16_f32 v190, v190, v1
	ds_write_b16 v161, v190 offset:272
	v_lshlrev_b32_e32 v190, 16, v229
	v_mul_f32_e32 v190, v237, v190
	v_cvt_pk_bf16_f32 v190, v190, v1
	ds_write_b16 v161, v190 offset:544
	v_and_b32_e32 v190, 0xffff0000, v229
	v_mul_f32_e32 v190, v237, v190
	v_cvt_pk_bf16_f32 v190, v190, v1
	ds_write_b16 v161, v190 offset:816
	v_lshlrev_b32_e32 v190, 16, v230
	v_mul_f32_e32 v190, v237, v190
	v_cvt_pk_bf16_f32 v190, v190, v1
	ds_write_b16 v161, v190 offset:1088
	v_and_b32_e32 v190, 0xffff0000, v230
	v_mul_f32_e32 v190, v237, v190
	v_cvt_pk_bf16_f32 v190, v190, v1
	ds_write_b16 v161, v190 offset:1360
	v_lshlrev_b32_e32 v190, 16, v231
	v_mul_f32_e32 v190, v237, v190
	v_cvt_pk_bf16_f32 v190, v190, v1
	ds_write_b16 v161, v190 offset:1632
	v_and_b32_e32 v190, 0xffff0000, v231
	v_mul_f32_e32 v190, v237, v190
	v_cvt_pk_bf16_f32 v190, v190, v1
	ds_write_b16 v161, v190 offset:1904
	s_waitcnt vmcnt(4)
	v_lshlrev_b32_e32 v190, 16, v232
	v_mul_f32_e32 v190, v237, v190
	v_cvt_pk_bf16_f32 v190, v190, v1
	ds_write_b16 v162, v190
	v_and_b32_e32 v190, 0xffff0000, v232
	v_mul_f32_e32 v190, v237, v190
	v_cvt_pk_bf16_f32 v190, v190, v1
	ds_write_b16 v162, v190 offset:272
	v_lshlrev_b32_e32 v190, 16, v233
	v_mul_f32_e32 v190, v237, v190
	v_cvt_pk_bf16_f32 v190, v190, v1
	ds_write_b16 v162, v190 offset:544
	v_and_b32_e32 v190, 0xffff0000, v233
	v_mul_f32_e32 v190, v237, v190
	v_cvt_pk_bf16_f32 v190, v190, v1
	ds_write_b16 v162, v190 offset:816
	v_lshlrev_b32_e32 v190, 16, v234
	v_mul_f32_e32 v190, v237, v190
	v_cvt_pk_bf16_f32 v190, v190, v1
	ds_write_b16 v162, v190 offset:1088
	v_and_b32_e32 v190, 0xffff0000, v234
	v_mul_f32_e32 v190, v237, v190
	v_cvt_pk_bf16_f32 v190, v190, v1
	ds_write_b16 v162, v190 offset:1360
	v_lshlrev_b32_e32 v190, 16, v235
	v_mul_f32_e32 v190, v237, v190
	v_cvt_pk_bf16_f32 v190, v190, v1
	ds_write_b16 v162, v190 offset:1632
	v_and_b32_e32 v190, 0xffff0000, v235
	v_mul_f32_e32 v190, v237, v190
	v_cvt_pk_bf16_f32 v190, v190, v1
	ds_write_b16 v162, v190 offset:1904
	s_waitcnt vmcnt(3)
	v_cvt_pk_bf16_f32 v244, v244, v245
	v_cvt_pk_bf16_f32 v245, v246, v247
	ds_write_b64 v163, v[244:245]
	s_waitcnt vmcnt(2)
	v_cvt_pk_bf16_f32 v248, v248, v249
	v_cvt_pk_bf16_f32 v249, v250, v251
	ds_write_b64 v164, v[248:249]
	s_waitcnt vmcnt(1)
	v_cvt_pk_bf16_f32 v252, v252, v253
	v_cvt_pk_bf16_f32 v253, v254, v255
	ds_write_b64 v165, v[252:253]
	s_waitcnt vmcnt(0)
	v_cvt_pk_bf16_f32 v216, v216, v217
	v_cvt_pk_bf16_f32 v217, v218, v219
	ds_write_b64 v166, v[216:217]
	s_waitcnt lgkmcnt(0)
	s_barrier
; DI int crow(int r, int h) { return (r & 3) + 8 * (r >> 2) + 4 * h; }
; #define MFMA32(a, b, c) __builtin_amdgcn_mfma_f32_32x32x16_bf16((a), (b), (c), 0, 0, 0)
; DI void ssd_out_unit(const Params& P, int layer, int b, int c, char* lds, int tid) {
;     ...
;         f32x16 y0 = {}, y1 = {};
; #pragma unroll
;         for (int ks = 0; ks < 8; ++ks) { const bf16x8 a = *(const bf16x8*)(CM + (32 * lb + r) * SP + 16 * ks + 8 * hh);
;             const bf16x8 b0 = *(const bf16x8*)(PV[0] + (32 * pb + r) * SP + 16 * ks + 8 * hh), b1 = *(const bf16x8*)(PV[1] + (32 * pb + r) * SP + 16 * ks + 8 * hh);
;             y0 = MFMA32(a, b0, y0); y1 = MFMA32(a, b1, y1); }
;         const float* ac0 = acs + (2 * g) * CH; const float* ac1 = ac0 + CH;
; #pragma unroll
;         for (int i = 0; i < 16; ++i) { const int l = 32 * lb + crow(i, hh); y0[i] *= __expf(ac0[l]); y1[i] *= __expf(ac1[l]); }
;         const float al0 = ac0[32 * lb + r], al1 = ac1[32 * lb + r];
;         for (int sbk = 0; sbk <= lb; ++sbk) {
	ds_read_b128 v[18:21], v151
	ds_read_b128 v[34:37], v151 offset:32
	ds_read_b128 v[2:5], v152
	ds_read_b128 v[38:41], v152 offset:32
	ds_read_b128 v[22:25], v153
	ds_read_b128 v[42:45], v153 offset:32
	s_waitcnt lgkmcnt(3)
	v_mfma_f32_32x32x16_bf16 v[2:17], v[18:21], v[2:5], 0
	s_waitcnt lgkmcnt(1)
	v_mfma_f32_32x32x16_bf16 v[18:33], v[18:21], v[22:25], 0
	v_mfma_f32_32x32x16_bf16 v[2:17], v[34:37], v[38:41], v[2:17]
	s_waitcnt lgkmcnt(0)
	v_mfma_f32_32x32x16_bf16 v[18:33], v[34:37], v[42:45], v[18:33]
	ds_read_b128 v[34:37], v151 offset:64
	ds_read_b128 v[38:41], v152 offset:64
	ds_read_b128 v[42:45], v153 offset:64
	ds_read_b128 v[216:219], v151 offset:96
	ds_read_b128 v[220:223], v152 offset:96
	ds_read_b128 v[224:227], v153 offset:96
	s_waitcnt lgkmcnt(4)
	v_mfma_f32_32x32x16_bf16 v[2:17], v[34:37], v[38:41], v[2:17]
	s_waitcnt lgkmcnt(3)
	v_mfma_f32_32x32x16_bf16 v[18:33], v[34:37], v[42:45], v[18:33]
	ds_read_b128 v[34:37], v151 offset:128
	ds_read_b128 v[38:41], v152 offset:128
	ds_read_b128 v[42:45], v153 offset:128
	s_waitcnt lgkmcnt(4)
	v_mfma_f32_32x32x16_bf16 v[2:17], v[216:219], v[220:223], v[2:17]
	s_waitcnt lgkmcnt(3)
	v_mfma_f32_32x32x16_bf16 v[18:33], v[216:219], v[224:227], v[18:33]
	ds_read_b128 v[216:219], v151 offset:160
	ds_read_b128 v[220:223], v152 offset:160
	ds_read_b128 v[224:227], v153 offset:160
	s_waitcnt lgkmcnt(4)
	v_mfma_f32_32x32x16_bf16 v[2:17], v[34:37], v[38:41], v[2:17]
	s_waitcnt lgkmcnt(3)
	v_mfma_f32_32x32x16_bf16 v[18:33], v[34:37], v[42:45], v[18:33]
	ds_read_b128 v[34:37], v151 offset:192
	ds_read_b128 v[38:41], v152 offset:192
	ds_read_b128 v[42:45], v153 offset:192
	s_waitcnt lgkmcnt(4)
	v_mfma_f32_32x32x16_bf16 v[2:17], v[216:219], v[220:223], v[2:17]
	s_waitcnt lgkmcnt(3)
	v_mfma_f32_32x32x16_bf16 v[18:33], v[216:219], v[224:227], v[18:33]
	ds_read_b128 v[216:219], v151 offset:224
	ds_read_b128 v[220:223], v152 offset:224
	ds_read_b128 v[224:227], v153 offset:224
	s_waitcnt lgkmcnt(4)
	v_mfma_f32_32x32x16_bf16 v[2:17], v[34:37], v[38:41], v[2:17]
	s_waitcnt lgkmcnt(3)
	v_mfma_f32_32x32x16_bf16 v[18:33], v[34:37], v[42:45], v[18:33]
	s_waitcnt lgkmcnt(1)
	v_mfma_f32_32x32x16_bf16 v[2:17], v[216:219], v[220:223], v[2:17]
	s_waitcnt lgkmcnt(0)
	v_mfma_f32_32x32x16_bf16 v[18:33], v[216:219], v[224:227], v[18:33]
	ds_read_b128 v[36:39], v174
	ds_read_b128 v[40:43], v174 offset:32
	ds_read_b128 v[134:137], v174 offset:512
	s_waitcnt lgkmcnt(2)
	v_mul_f32_e32 v34, 0x3fb8aa3b, v36
	v_exp_f32_e32 v46, v34
	s_waitcnt lgkmcnt(0)
	v_mul_f32_e32 v34, 0x3fb8aa3b, v134
	v_exp_f32_e32 v36, v34
	v_mul_f32_e32 v34, 0x3fb8aa3b, v37
	v_exp_f32_e32 v47, v34
	v_mul_f32_e32 v34, 0x3fb8aa3b, v135
	v_exp_f32_e32 v37, v34
	v_mul_f32_e32 v34, 0x3fb8aa3b, v38
	v_mul_f32_e32 v35, 0x3fb8aa3b, v39
	v_exp_f32_e32 v48, v34
	v_mul_f32_e32 v34, 0x3fb8aa3b, v136
	v_exp_f32_e32 v49, v35
	v_mul_f32_e32 v35, 0x3fb8aa3b, v137
	ds_read_b128 v[136:139], v174 offset:544
	v_mul_f32_e32 v38, 0x3fb8aa3b, v40
	v_mul_f32_e32 v39, 0x3fb8aa3b, v41
	v_mul_f32_e32 v40, 0x3fb8aa3b, v42
	v_mul_f32_e32 v41, 0x3fb8aa3b, v43
	ds_read_b128 v[42:45], v174 offset:64
	v_exp_f32_e32 v134, v38
	s_waitcnt lgkmcnt(1)
	v_mul_f32_e32 v38, 0x3fb8aa3b, v136
	v_exp_f32_e32 v135, v39
	v_mul_f32_e32 v39, 0x3fb8aa3b, v137
	v_exp_f32_e32 v136, v40
	v_mul_f32_e32 v40, 0x3fb8aa3b, v138
	v_exp_f32_e32 v137, v41
	v_mul_f32_e32 v41, 0x3fb8aa3b, v139
	ds_read_b128 v[138:141], v174 offset:576
	s_waitcnt lgkmcnt(1)
	v_mul_f32_e32 v42, 0x3fb8aa3b, v42
	v_mul_f32_e32 v43, 0x3fb8aa3b, v43
	v_mul_f32_e32 v44, 0x3fb8aa3b, v44
	v_mul_f32_e32 v45, 0x3fb8aa3b, v45
	v_exp_f32_e32 v142, v42
	s_waitcnt lgkmcnt(0)
	v_mul_f32_e32 v42, 0x3fb8aa3b, v138
	v_exp_f32_e32 v143, v43
	v_mul_f32_e32 v43, 0x3fb8aa3b, v139
	v_exp_f32_e32 v190, v44
	v_mul_f32_e32 v44, 0x3fb8aa3b, v140
	v_exp_f32_e32 v191, v45
	v_mul_f32_e32 v45, 0x3fb8aa3b, v141
	ds_read_b128 v[138:141], v174 offset:96
	ds_read_b128 v[174:177], v174 offset:608
	v_pk_mul_f32 v[2:3], v[2:3], v[46:47]
	v_exp_f32_e32 v34, v34
	v_exp_f32_e32 v35, v35
	s_waitcnt lgkmcnt(1)
	v_mul_f32_e32 v138, 0x3fb8aa3b, v138
	v_mul_f32_e32 v139, 0x3fb8aa3b, v139
	v_mul_f32_e32 v140, 0x3fb8aa3b, v140
	v_exp_f32_e32 v192, v138
	s_waitcnt lgkmcnt(0)
	v_mul_f32_e32 v138, 0x3fb8aa3b, v174
	v_exp_f32_e32 v193, v139
	v_mul_f32_e32 v139, 0x3fb8aa3b, v175
	v_exp_f32_e32 v174, v140
	v_mul_f32_e32 v140, 0x3fb8aa3b, v176
	v_mul_f32_e32 v141, 0x3fb8aa3b, v141
	v_mul_f32_e32 v46, 0x3fb8aa3b, v177
	v_exp_f32_e32 v38, v38
	v_exp_f32_e32 v39, v39
	v_exp_f32_e32 v40, v40
	v_exp_f32_e32 v41, v41
	v_exp_f32_e32 v42, v42
	v_exp_f32_e32 v43, v43
	v_exp_f32_e32 v44, v44
	v_exp_f32_e32 v45, v45
	v_exp_f32_e32 v138, v138
	v_exp_f32_e32 v139, v139
	v_exp_f32_e32 v140, v140
	v_exp_f32_e32 v175, v141
	v_exp_f32_e32 v141, v46
	v_pk_mul_f32 v[14:15], v[14:15], v[192:193]
	v_pk_mul_f32 v[12:13], v[12:13], v[190:191]
	v_pk_mul_f32 v[16:17], v[16:17], v[174:175]
	v_pk_mul_f32 v[10:11], v[10:11], v[142:143]
	v_pk_mul_f32 v[8:9], v[8:9], v[136:137]
	v_pk_mul_f32 v[6:7], v[6:7], v[134:135]
	v_pk_mul_f32 v[4:5], v[4:5], v[48:49]
	v_pk_mul_f32 v[18:19], v[18:19], v[36:37]
	v_pk_mul_f32 v[32:33], v[32:33], v[140:141]
	v_pk_mul_f32 v[30:31], v[30:31], v[138:139]
	v_pk_mul_f32 v[28:29], v[28:29], v[44:45]
	v_pk_mul_f32 v[26:27], v[26:27], v[42:43]
	v_pk_mul_f32 v[24:25], v[24:25], v[40:41]
	v_pk_mul_f32 v[22:23], v[22:23], v[38:39]
	v_pk_mul_f32 v[20:21], v[20:21], v[34:35]
	s_and_saveexec_b64 s[56:57], s[54:55]
	s_cbranch_execz .LBB0_368
	v_lshl_add_u32 v34, v149, 2, s16
	ds_read2st64_b32 v[134:135], v34 offset1:2
	v_add_u32_e32 v136, s13, v150
	s_mov_b64 s[58:59], 0
	v_mov_b32_e32 v137, v173
	v_mov_b32_e32 v138, v172
	v_mov_b32_e32 v139, v171
	v_mov_b32_e32 v140, v170
	s_branch .LBB0_372
